# fused out-projection K-loop: the twelve P1/P3 LDS-DMA loads in scalar-base form too (12 of its 16 64-bit VALU address adds removed)
# speedup vs baseline: 1.0057x; 1.0006x over previous
.Lpadj_16:
	s_waitcnt vmcnt(8)
	s_waitcnt lgkmcnt(0)
	s_barrier
	v_mfma_f32_16x16x32_bf16 v[126:129], v[148:151], v[180:183], v[126:129]
	v_mfma_f32_16x16x32_bf16 v[122:125], v[156:159], v[180:183], v[122:125]
	v_mfma_f32_16x16x32_bf16 v[110:113], v[148:151], v[188:191], v[110:113]
	v_mfma_f32_16x16x32_bf16 v[106:109], v[156:159], v[188:191], v[106:109]
	v_mfma_f32_16x16x32_bf16 v[94:97], v[148:151], v[196:199], v[94:97]
	v_mfma_f32_16x16x32_bf16 v[90:93], v[156:159], v[196:199], v[90:93]
	v_mfma_f32_16x16x32_bf16 v[78:81], v[148:151], v[204:207], v[78:81]
	v_mfma_f32_16x16x32_bf16 v[74:77], v[156:159], v[204:207], v[74:77]
	v_mfma_f32_16x16x32_bf16 v[126:129], v[152:155], v[184:187], v[126:129]
	v_mfma_f32_16x16x32_bf16 v[122:125], v[160:163], v[184:187], v[122:125]
	v_mfma_f32_16x16x32_bf16 v[110:113], v[152:155], v[192:195], v[110:113]
	v_mfma_f32_16x16x32_bf16 v[106:109], v[160:163], v[192:195], v[106:109]
	v_mfma_f32_16x16x32_bf16 v[94:97], v[152:155], v[200:203], v[94:97]
	v_mfma_f32_16x16x32_bf16 v[90:93], v[160:163], v[200:203], v[90:93]
	v_mfma_f32_16x16x32_bf16 v[78:81], v[152:155], v[220:223], v[78:81]
	v_mfma_f32_16x16x32_bf16 v[74:77], v[160:163], v[220:223], v[74:77]
	v_mfma_f32_16x16x32_bf16 v[118:121], v[164:167], v[180:183], v[118:121]
	v_mfma_f32_16x16x32_bf16 v[114:117], v[172:175], v[180:183], v[114:117]
	v_mfma_f32_16x16x32_bf16 v[102:105], v[164:167], v[188:191], v[102:105]
	v_mfma_f32_16x16x32_bf16 v[98:101], v[172:175], v[188:191], v[98:101]
	v_mfma_f32_16x16x32_bf16 v[86:89], v[164:167], v[196:199], v[86:89]
	v_mfma_f32_16x16x32_bf16 v[82:85], v[172:175], v[196:199], v[82:85]
	v_mfma_f32_16x16x32_bf16 v[70:73], v[164:167], v[204:207], v[70:73]
	v_mfma_f32_16x16x32_bf16 v[66:69], v[172:175], v[204:207], v[66:69]
	v_mfma_f32_16x16x32_bf16 v[118:121], v[168:171], v[184:187], v[118:121]
	v_mfma_f32_16x16x32_bf16 v[114:117], v[176:179], v[184:187], v[114:117]
	v_mfma_f32_16x16x32_bf16 v[102:105], v[168:171], v[192:195], v[102:105]
	v_mfma_f32_16x16x32_bf16 v[98:101], v[176:179], v[192:195], v[98:101]
	v_mfma_f32_16x16x32_bf16 v[86:89], v[168:171], v[200:203], v[86:89]
	v_mfma_f32_16x16x32_bf16 v[82:85], v[176:179], v[200:203], v[82:85]
	v_mfma_f32_16x16x32_bf16 v[70:73], v[168:171], v[220:223], v[70:73]
	v_mfma_f32_16x16x32_bf16 v[66:69], v[176:179], v[220:223], v[66:69]
	s_barrier
	s_add_i32 s66, s66, s47
	s_mov_b32 m0, s66
	ds_read_b128 v[180:183], v147 offset:16384
	ds_read_b128 v[184:187], v147 offset:17408
	ds_read_b128 v[188:191], v147 offset:18432
	ds_read_b128 v[192:195], v147 offset:19456
	ds_read_b128 v[196:199], v147 offset:20480
	ds_read_b128 v[200:203], v147 offset:21504
	ds_read_b128 v[204:207], v147 offset:22528
	ds_read_b128 v[220:223], v147 offset:23552
	global_load_lds_dwordx4 v132, s[64:65]
	s_add_i32 m0, s66, 0x2000
	s_mov_b64 s[100:101], s[64:65]
	s_add_u32 s64, s64, s45
	s_addc_u32 s65, s65, 0
	s_add_i32 s31, s31, s47
	global_load_lds_dwordx4 v136, s[100:101]
	s_mov_b32 m0, s31
	s_nop 0
	global_load_lds_dwordx4 v132, s[64:65]
	s_add_i32 m0, s31, 0x2000
	s_nop 0
	global_load_lds_dwordx4 v136, s[64:65]
	s_mov_b32 m0, s51
	s_nop 0
	global_load_lds_dwordx4 v130, s[38:39]
	s_mov_b32 m0, s52
	s_nop 0
	global_load_lds_dwordx4 v134, s[38:39]
	s_branch .Lpadj_17
	s_nop 0
	s_nop 0
	s_nop 0
	s_nop 0
	s_nop 0
	s_nop 0
	s_nop 0
	s_nop 0
	s_nop 0
	s_nop 0
	s_nop 0
	s_nop 0
	s_nop 0
	s_nop 0

.Lpadj_18:
	s_waitcnt vmcnt(8)
	s_waitcnt lgkmcnt(0)
	s_barrier
	v_mfma_f32_16x16x32_bf16 v[126:129], v[148:151], v[180:183], v[126:129]
	v_mfma_f32_16x16x32_bf16 v[122:125], v[156:159], v[180:183], v[122:125]
	v_mfma_f32_16x16x32_bf16 v[110:113], v[148:151], v[188:191], v[110:113]
	v_mfma_f32_16x16x32_bf16 v[106:109], v[156:159], v[188:191], v[106:109]
	v_mfma_f32_16x16x32_bf16 v[94:97], v[148:151], v[196:199], v[94:97]
	v_mfma_f32_16x16x32_bf16 v[90:93], v[156:159], v[196:199], v[90:93]
	v_mfma_f32_16x16x32_bf16 v[78:81], v[148:151], v[204:207], v[78:81]
	v_mfma_f32_16x16x32_bf16 v[74:77], v[156:159], v[204:207], v[74:77]
	v_mfma_f32_16x16x32_bf16 v[126:129], v[152:155], v[184:187], v[126:129]
	v_mfma_f32_16x16x32_bf16 v[122:125], v[160:163], v[184:187], v[122:125]
	v_mfma_f32_16x16x32_bf16 v[110:113], v[152:155], v[192:195], v[110:113]
	v_mfma_f32_16x16x32_bf16 v[106:109], v[160:163], v[192:195], v[106:109]
	v_mfma_f32_16x16x32_bf16 v[94:97], v[152:155], v[200:203], v[94:97]
	v_mfma_f32_16x16x32_bf16 v[90:93], v[160:163], v[200:203], v[90:93]
	v_mfma_f32_16x16x32_bf16 v[78:81], v[152:155], v[220:223], v[78:81]
	v_mfma_f32_16x16x32_bf16 v[74:77], v[160:163], v[220:223], v[74:77]
	v_mfma_f32_16x16x32_bf16 v[118:121], v[164:167], v[180:183], v[118:121]
	v_mfma_f32_16x16x32_bf16 v[114:117], v[172:175], v[180:183], v[114:117]
	v_mfma_f32_16x16x32_bf16 v[102:105], v[164:167], v[188:191], v[102:105]
	v_mfma_f32_16x16x32_bf16 v[98:101], v[172:175], v[188:191], v[98:101]
	v_mfma_f32_16x16x32_bf16 v[86:89], v[164:167], v[196:199], v[86:89]
	v_mfma_f32_16x16x32_bf16 v[82:85], v[172:175], v[196:199], v[82:85]
	v_mfma_f32_16x16x32_bf16 v[70:73], v[164:167], v[204:207], v[70:73]
	v_mfma_f32_16x16x32_bf16 v[66:69], v[172:175], v[204:207], v[66:69]
	v_mfma_f32_16x16x32_bf16 v[118:121], v[168:171], v[184:187], v[118:121]
	v_mfma_f32_16x16x32_bf16 v[114:117], v[176:179], v[184:187], v[114:117]
	v_mfma_f32_16x16x32_bf16 v[102:105], v[168:171], v[192:195], v[102:105]
	v_mfma_f32_16x16x32_bf16 v[98:101], v[176:179], v[192:195], v[98:101]
	v_mfma_f32_16x16x32_bf16 v[86:89], v[168:171], v[200:203], v[86:89]
	v_mfma_f32_16x16x32_bf16 v[82:85], v[176:179], v[200:203], v[82:85]
	v_mfma_f32_16x16x32_bf16 v[70:73], v[168:171], v[220:223], v[70:73]
	v_mfma_f32_16x16x32_bf16 v[66:69], v[176:179], v[220:223], v[66:69]
	s_barrier
	s_add_i32 s31, s31, s47
	s_add_u32 s100, s100, 0x80
	s_addc_u32 s101, s101, 0
	s_mov_b32 m0, s31
	ds_read_b128 v[180:183], v147 offset:49152
	ds_read_b128 v[184:187], v147 offset:50176
	ds_read_b128 v[188:191], v147 offset:51200
	ds_read_b128 v[192:195], v147 offset:52224
	ds_read_b128 v[196:199], v147 offset:53248
	ds_read_b128 v[200:203], v147 offset:54272
	ds_read_b128 v[204:207], v147 offset:55296
	ds_read_b128 v[220:223], v147 offset:56320
	global_load_lds_dwordx4 v132, s[100:101]
	s_add_i32 m0, s31, 0x2000
	s_add_i32 s31, s64, s47
	global_load_lds_dwordx4 v136, s[100:101]
	s_add_u32 s100, s100, s45
	s_addc_u32 s101, s101, 0
	s_mov_b32 m0, s31
	s_nop 0
	global_load_lds_dwordx4 v132, s[100:101]
	s_add_i32 m0, s31, 0x2000
	s_nop 0
	global_load_lds_dwordx4 v136, s[100:101]
	s_sub_u32 s38, s38, s45
	s_subb_u32 s39, s39, 0
	s_add_u32 s38, s38, 0x80
	s_addc_u32 s39, s39, 0
	s_mov_b32 m0, s57
	s_nop 0
	global_load_lds_dwordx4 v130, s[38:39]
	s_mov_b32 m0, s58
	s_nop 0
	global_load_lds_dwordx4 v134, s[38:39]
	s_branch .Lpadj_19
	s_nop 0
	s_nop 0
	s_nop 0
	s_nop 0
	s_nop 0
	s_nop 0
	s_nop 0
